# hand-written epi_tables (w_in, ffn_in phases): closed-form unit decode, all units' loads in flight
# speedup vs baseline: 1.0462x; 1.0038x over previous
.LBB0_111:
	s_add_i32 s0, s74, -2
	s_mul_hi_i32 s1, s0, 0x2aaaaaab
	s_lshr_b32 s2, s1, 31
	s_add_i32 s28, s1, s2
	s_mov_b32 s2, s28
	v_writelane_b32 v255, s2, 36
	s_mul_i32 s1, s28, 6
	s_mov_b64 s[66:67], 0
	v_writelane_b32 v255, s3, 37
	s_sub_i32 s2, s0, s1
	v_writelane_b32 v255, s2, 38
	s_cmp_lt_i32 s2, 2
	s_mov_b64 s[2:3], 0
	v_writelane_b32 v255, s2, 39
	s_mov_b64 s[0:1], -1
	s_mov_b32 s91, s74
	v_writelane_b32 v255, s3, 40
	s_cbranch_scc1 .LBB0_386
	v_readlane_b32 s0, v255, 38
	s_cmp_gt_i32 s0, 2
	s_cbranch_scc0 .LBB0_169
	s_cmp_gt_i32 s0, 3
	s_cbranch_scc0 .LBB0_170
	s_cmp_eq_u32 s0, 4
	s_mov_b64 s[0:1], -1
	s_cbranch_scc0 .LBB0_172
	s_ashr_i32 s33, s30, 31
	s_cmpk_lt_i32 s30, 0x2c0
	s_waitcnt lgkmcnt(0)
	v_mov_b32_e32 v1, v228
	s_cselect_b64 s[0:1], -1, 0
	s_cmpk_gt_i32 s30, 0x2bf
	s_cbranch_scc1 .LBB0_151
	v_readfirstlane_b32 s36, v228
	s_nop 3
	s_cmp_lt_u32 s36, 0x100
	s_cbranch_scc0 .Lepi4_bias
	s_mov_b32 s28, s30
	s_mov_b32 s29, 0
	v_lshlrev_b32_e32 v0, 7, v228
	v_lshl_add_u32 v3, v228, 2, v246
.Lepi4_rb:
	s_add_i32 s36, s29, 0
	s_cmp_lt_u32 s36, 7
	s_cbranch_scc0 .Lepi4_rl0
	s_mul_i32 s37, s68, 0
	s_add_i32 s37, s37, s28
	s_cmp_lt_u32 s37, 0x2c0
	s_cbranch_scc0 .Lepi4_rl0
	s_and_b32 s38, s37, 7
	s_lshl_b32 s38, s38, 2
	s_bfe_u32 s39, s37, 0x20003
	s_add_u32 s38, s38, s39
	s_lshl_b32 s38, s38, 15
	v_add_u32_e32 v2, s38, v0
	s_nop 0
	global_load_dwordx4 v[8:11], v2, s[16:17]
	global_load_dwordx4 v[12:15], v2, s[16:17] offset:16
	global_load_dwordx4 v[16:19], v2, s[16:17] offset:32
	global_load_dwordx4 v[20:23], v2, s[16:17] offset:48
	global_load_dwordx4 v[24:27], v2, s[16:17] offset:64
	global_load_dwordx4 v[28:31], v2, s[16:17] offset:80
	global_load_dwordx4 v[32:35], v2, s[16:17] offset:96
	global_load_dwordx4 v[36:39], v2, s[16:17] offset:112
.Lepi4_rl0:
	s_add_i32 s36, s29, 1
	s_cmp_lt_u32 s36, 7
	s_cbranch_scc0 .Lepi4_rl1
	s_mul_i32 s37, s68, 1
	s_add_i32 s37, s37, s28
	s_cmp_lt_u32 s37, 0x2c0
	s_cbranch_scc0 .Lepi4_rl1
	s_and_b32 s38, s37, 7
	s_lshl_b32 s38, s38, 2
	s_bfe_u32 s39, s37, 0x20003
	s_add_u32 s38, s38, s39
	s_lshl_b32 s38, s38, 15
	v_add_u32_e32 v2, s38, v0
	s_nop 0
	global_load_dwordx4 v[40:43], v2, s[16:17]
	global_load_dwordx4 v[44:47], v2, s[16:17] offset:16
	global_load_dwordx4 v[48:51], v2, s[16:17] offset:32
	global_load_dwordx4 v[52:55], v2, s[16:17] offset:48
	global_load_dwordx4 v[56:59], v2, s[16:17] offset:64
	global_load_dwordx4 v[60:63], v2, s[16:17] offset:80
	global_load_dwordx4 v[64:67], v2, s[16:17] offset:96
	global_load_dwordx4 v[68:71], v2, s[16:17] offset:112
.Lepi4_rl1:
	s_add_i32 s36, s29, 2
	s_cmp_lt_u32 s36, 7
	s_cbranch_scc0 .Lepi4_rl2
	s_mul_i32 s37, s68, 2
	s_add_i32 s37, s37, s28
	s_cmp_lt_u32 s37, 0x2c0
	s_cbranch_scc0 .Lepi4_rl2
	s_and_b32 s38, s37, 7
	s_lshl_b32 s38, s38, 2
	s_bfe_u32 s39, s37, 0x20003
	s_add_u32 s38, s38, s39
	s_lshl_b32 s38, s38, 15
	v_add_u32_e32 v2, s38, v0
	s_nop 0
	global_load_dwordx4 v[72:75], v2, s[16:17]
	global_load_dwordx4 v[76:79], v2, s[16:17] offset:16
	global_load_dwordx4 v[80:83], v2, s[16:17] offset:32
	global_load_dwordx4 v[84:87], v2, s[16:17] offset:48
	global_load_dwordx4 v[88:91], v2, s[16:17] offset:64
	global_load_dwordx4 v[92:95], v2, s[16:17] offset:80
	global_load_dwordx4 v[96:99], v2, s[16:17] offset:96
	global_load_dwordx4 v[100:103], v2, s[16:17] offset:112
.Lepi4_rl2:
	s_waitcnt vmcnt(0)
	s_add_i32 s36, s29, 0
	s_cmp_lt_u32 s36, 7
	s_cbranch_scc0 .Lepi4_rs0
	s_mul_i32 s37, s68, 0
	s_add_i32 s37, s37, s28
	s_cmp_lt_u32 s37, 0x2c0
	s_cbranch_scc0 .Lepi4_rs0
	v_add_f32_e32 v8, v8, v24
	v_add_f32_e32 v9, v9, v25
	v_add_f32_e32 v10, v10, v26
	v_add_f32_e32 v11, v11, v27
	v_add_f32_e32 v12, v12, v28
	v_add_f32_e32 v13, v13, v29
	v_add_f32_e32 v14, v14, v30
	v_add_f32_e32 v15, v15, v31
	v_add_f32_e32 v16, v16, v32
	v_add_f32_e32 v17, v17, v33
	v_add_f32_e32 v18, v18, v34
	v_add_f32_e32 v19, v19, v35
	v_add_f32_e32 v20, v20, v36
	v_add_f32_e32 v21, v21, v37
	v_add_f32_e32 v22, v22, v38
	v_add_f32_e32 v23, v23, v39
	v_add_f32_e32 v8, v8, v16
	v_add_f32_e32 v9, v9, v17
	v_add_f32_e32 v10, v10, v18
	v_add_f32_e32 v11, v11, v19
	v_add_f32_e32 v12, v12, v20
	v_add_f32_e32 v13, v13, v21
	v_add_f32_e32 v14, v14, v22
	v_add_f32_e32 v15, v15, v23
	v_add_f32_e32 v8, v8, v12
	v_add_f32_e32 v9, v9, v13
	v_add_f32_e32 v10, v10, v14
	v_add_f32_e32 v11, v11, v15
	v_add_f32_e32 v8, v8, v10
	v_add_f32_e32 v9, v9, v11
	v_add_f32_e32 v8, v8, v9
	v_fmamk_f32 v1, v8, 0x3a800000, v250
	v_cmp_gt_f32_e32 vcc, s94, v1
	v_mul_f32_e32 v4, 0x4b800000, v1
	s_nop 1
	v_cndmask_b32_e32 v1, v1, v4, vcc
	v_rsq_f32_e32 v1, v1
	s_lshl_b32 s36, s36, 10
	v_add_u32_e32 v5, s36, v3
	v_mul_f32_e32 v4, 0x45800000, v1
	v_cndmask_b32_e32 v1, v1, v4, vcc
	ds_write_b32 v5, v1
.Lepi4_rs0:
	s_add_i32 s36, s29, 1
	s_cmp_lt_u32 s36, 7
	s_cbranch_scc0 .Lepi4_rs1
	s_mul_i32 s37, s68, 1
	s_add_i32 s37, s37, s28
	s_cmp_lt_u32 s37, 0x2c0
	s_cbranch_scc0 .Lepi4_rs1
	v_add_f32_e32 v40, v40, v56
	v_add_f32_e32 v41, v41, v57
	v_add_f32_e32 v42, v42, v58
	v_add_f32_e32 v43, v43, v59
	v_add_f32_e32 v44, v44, v60
	v_add_f32_e32 v45, v45, v61
	v_add_f32_e32 v46, v46, v62
	v_add_f32_e32 v47, v47, v63
	v_add_f32_e32 v48, v48, v64
	v_add_f32_e32 v49, v49, v65
	v_add_f32_e32 v50, v50, v66
	v_add_f32_e32 v51, v51, v67
	v_add_f32_e32 v52, v52, v68
	v_add_f32_e32 v53, v53, v69
	v_add_f32_e32 v54, v54, v70
	v_add_f32_e32 v55, v55, v71
	v_add_f32_e32 v40, v40, v48
	v_add_f32_e32 v41, v41, v49
	v_add_f32_e32 v42, v42, v50
	v_add_f32_e32 v43, v43, v51
	v_add_f32_e32 v44, v44, v52
	v_add_f32_e32 v45, v45, v53
	v_add_f32_e32 v46, v46, v54
	v_add_f32_e32 v47, v47, v55
	v_add_f32_e32 v40, v40, v44
	v_add_f32_e32 v41, v41, v45
	v_add_f32_e32 v42, v42, v46
	v_add_f32_e32 v43, v43, v47
	v_add_f32_e32 v40, v40, v42
	v_add_f32_e32 v41, v41, v43
	v_add_f32_e32 v40, v40, v41
	v_fmamk_f32 v1, v40, 0x3a800000, v250
	v_cmp_gt_f32_e32 vcc, s94, v1
	v_mul_f32_e32 v4, 0x4b800000, v1
	s_nop 1
	v_cndmask_b32_e32 v1, v1, v4, vcc
	v_rsq_f32_e32 v1, v1
	s_lshl_b32 s36, s36, 10
	v_add_u32_e32 v5, s36, v3
	v_mul_f32_e32 v4, 0x45800000, v1
	v_cndmask_b32_e32 v1, v1, v4, vcc
	ds_write_b32 v5, v1
.Lepi4_rs1:
	s_add_i32 s36, s29, 2
	s_cmp_lt_u32 s36, 7
	s_cbranch_scc0 .Lepi4_rs2
	s_mul_i32 s37, s68, 2
	s_add_i32 s37, s37, s28
	s_cmp_lt_u32 s37, 0x2c0
	s_cbranch_scc0 .Lepi4_rs2
	v_add_f32_e32 v72, v72, v88
	v_add_f32_e32 v73, v73, v89
	v_add_f32_e32 v74, v74, v90
	v_add_f32_e32 v75, v75, v91
	v_add_f32_e32 v76, v76, v92
	v_add_f32_e32 v77, v77, v93
	v_add_f32_e32 v78, v78, v94
	v_add_f32_e32 v79, v79, v95
	v_add_f32_e32 v80, v80, v96
	v_add_f32_e32 v81, v81, v97
	v_add_f32_e32 v82, v82, v98
	v_add_f32_e32 v83, v83, v99
	v_add_f32_e32 v84, v84, v100
	v_add_f32_e32 v85, v85, v101
	v_add_f32_e32 v86, v86, v102
	v_add_f32_e32 v87, v87, v103
	v_add_f32_e32 v72, v72, v80
	v_add_f32_e32 v73, v73, v81
	v_add_f32_e32 v74, v74, v82
	v_add_f32_e32 v75, v75, v83
	v_add_f32_e32 v76, v76, v84
	v_add_f32_e32 v77, v77, v85
	v_add_f32_e32 v78, v78, v86
	v_add_f32_e32 v79, v79, v87
	v_add_f32_e32 v72, v72, v76
	v_add_f32_e32 v73, v73, v77
	v_add_f32_e32 v74, v74, v78
	v_add_f32_e32 v75, v75, v79
	v_add_f32_e32 v72, v72, v74
	v_add_f32_e32 v73, v73, v75
	v_add_f32_e32 v72, v72, v73
	v_fmamk_f32 v1, v72, 0x3a800000, v250
	v_cmp_gt_f32_e32 vcc, s94, v1
	v_mul_f32_e32 v4, 0x4b800000, v1
	s_nop 1
	v_cndmask_b32_e32 v1, v1, v4, vcc
	v_rsq_f32_e32 v1, v1
	s_lshl_b32 s36, s36, 10
	v_add_u32_e32 v5, s36, v3
	v_mul_f32_e32 v4, 0x45800000, v1
	v_cndmask_b32_e32 v1, v1, v4, vcc
	ds_write_b32 v5, v1
.Lepi4_rs2:
	s_add_i32 s29, s29, 3
	s_mul_i32 s36, s68, 3
	s_add_i32 s28, s28, s36
	s_cmp_lt_u32 s29, 7
	s_cbranch_scc0 .Lepi4_done
	s_cmp_lt_u32 s28, 0x2c0
	s_cbranch_scc1 .Lepi4_rb
	s_branch .Lepi4_done
.Lepi4_bias:
	v_readlane_b32 s36, v255, 36
	s_nop 3
	s_mul_i32 s36, s36, 0x1b800
	s_add_u32 s40, s10, s36
	s_addc_u32 s41, s11, 0
	v_add_u32_e32 v2, 0xffffff00, v228
	v_and_b32_e32 v3, 0x7f, v2
	v_lshrrev_b32_e32 v4, 7, v2
	v_mul_u32_u24_e32 v4, 0xb00, v4
	v_add_u32_e32 v3, v3, v4
	v_lshlrev_b32_e32 v3, 2, v3
	v_lshl_add_u32 v5, v2, 2, v246
	v_add_u32_e32 v5, 0x1c00, v5
	s_mul_i32 s37, s68, 0
	s_add_i32 s37, s37, s30
	s_cmp_lt_u32 s37, 0x2c0
	s_cbranch_scc0 .Lepi4_bw
	s_and_b32 s38, s37, 7
	s_lshl_b32 s38, s38, 2
	s_bfe_u32 s39, s37, 0x20003
	s_add_u32 s38, s38, s39
	s_lshr_b32 s39, s37, 5
	s_sub_i32 s42, s38, 16
	s_ashr_i32 s42, s42, 2
	s_add_i32 s42, s42, 1
	s_cmp_lt_i32 s38, 16
	s_cselect_b32 s42, 0, s42
	s_mul_i32 s42, s42, 0x1600
	s_lshl_b32 s39, s39, 7
	s_add_i32 s42, s42, s39
	s_lshl_b32 s42, s42, 2
	v_add_u32_e32 v20, s42, v3
	s_nop 0
	global_load_dword v10, v20, s[40:41]
	s_mul_i32 s37, s68, 1
	s_add_i32 s37, s37, s30
	s_cmp_lt_u32 s37, 0x2c0
	s_cbranch_scc0 .Lepi4_bw
	s_and_b32 s38, s37, 7
	s_lshl_b32 s38, s38, 2
	s_bfe_u32 s39, s37, 0x20003
	s_add_u32 s38, s38, s39
	s_lshr_b32 s39, s37, 5
	s_sub_i32 s42, s38, 16
	s_ashr_i32 s42, s42, 2
	s_add_i32 s42, s42, 1
	s_cmp_lt_i32 s38, 16
	s_cselect_b32 s42, 0, s42
	s_mul_i32 s42, s42, 0x1600
	s_lshl_b32 s39, s39, 7
	s_add_i32 s42, s42, s39
	s_lshl_b32 s42, s42, 2
	v_add_u32_e32 v21, s42, v3
	s_nop 0
	global_load_dword v11, v21, s[40:41]
	s_mul_i32 s37, s68, 2
	s_add_i32 s37, s37, s30
	s_cmp_lt_u32 s37, 0x2c0
	s_cbranch_scc0 .Lepi4_bw
	s_and_b32 s38, s37, 7
	s_lshl_b32 s38, s38, 2
	s_bfe_u32 s39, s37, 0x20003
	s_add_u32 s38, s38, s39
	s_lshr_b32 s39, s37, 5
	s_sub_i32 s42, s38, 16
	s_ashr_i32 s42, s42, 2
	s_add_i32 s42, s42, 1
	s_cmp_lt_i32 s38, 16
	s_cselect_b32 s42, 0, s42
	s_mul_i32 s42, s42, 0x1600
	s_lshl_b32 s39, s39, 7
	s_add_i32 s42, s42, s39
	s_lshl_b32 s42, s42, 2
	v_add_u32_e32 v22, s42, v3
	s_nop 0
	global_load_dword v12, v22, s[40:41]
	s_mul_i32 s37, s68, 3
	s_add_i32 s37, s37, s30
	s_cmp_lt_u32 s37, 0x2c0
	s_cbranch_scc0 .Lepi4_bw
	s_and_b32 s38, s37, 7
	s_lshl_b32 s38, s38, 2
	s_bfe_u32 s39, s37, 0x20003
	s_add_u32 s38, s38, s39
	s_lshr_b32 s39, s37, 5
	s_sub_i32 s42, s38, 16
	s_ashr_i32 s42, s42, 2
	s_add_i32 s42, s42, 1
	s_cmp_lt_i32 s38, 16
	s_cselect_b32 s42, 0, s42
	s_mul_i32 s42, s42, 0x1600
	s_lshl_b32 s39, s39, 7
	s_add_i32 s42, s42, s39
	s_lshl_b32 s42, s42, 2
	v_add_u32_e32 v23, s42, v3
	s_nop 0
	global_load_dword v13, v23, s[40:41]
	s_mul_i32 s37, s68, 4
	s_add_i32 s37, s37, s30
	s_cmp_lt_u32 s37, 0x2c0
	s_cbranch_scc0 .Lepi4_bw
	s_and_b32 s38, s37, 7
	s_lshl_b32 s38, s38, 2
	s_bfe_u32 s39, s37, 0x20003
	s_add_u32 s38, s38, s39
	s_lshr_b32 s39, s37, 5
	s_sub_i32 s42, s38, 16
	s_ashr_i32 s42, s42, 2
	s_add_i32 s42, s42, 1
	s_cmp_lt_i32 s38, 16
	s_cselect_b32 s42, 0, s42
	s_mul_i32 s42, s42, 0x1600
	s_lshl_b32 s39, s39, 7
	s_add_i32 s42, s42, s39
	s_lshl_b32 s42, s42, 2
	v_add_u32_e32 v24, s42, v3
	s_nop 0
	global_load_dword v14, v24, s[40:41]
	s_mul_i32 s37, s68, 5
	s_add_i32 s37, s37, s30
	s_cmp_lt_u32 s37, 0x2c0
	s_cbranch_scc0 .Lepi4_bw
	s_and_b32 s38, s37, 7
	s_lshl_b32 s38, s38, 2
	s_bfe_u32 s39, s37, 0x20003
	s_add_u32 s38, s38, s39
	s_lshr_b32 s39, s37, 5
	s_sub_i32 s42, s38, 16
	s_ashr_i32 s42, s42, 2
	s_add_i32 s42, s42, 1
	s_cmp_lt_i32 s38, 16
	s_cselect_b32 s42, 0, s42
	s_mul_i32 s42, s42, 0x1600
	s_lshl_b32 s39, s39, 7
	s_add_i32 s42, s42, s39
	s_lshl_b32 s42, s42, 2
	v_add_u32_e32 v25, s42, v3
	s_nop 0
	global_load_dword v15, v25, s[40:41]
	s_mul_i32 s37, s68, 6
	s_add_i32 s37, s37, s30
	s_cmp_lt_u32 s37, 0x2c0
	s_cbranch_scc0 .Lepi4_bw
	s_and_b32 s38, s37, 7
	s_lshl_b32 s38, s38, 2
	s_bfe_u32 s39, s37, 0x20003
	s_add_u32 s38, s38, s39
	s_lshr_b32 s39, s37, 5
	s_sub_i32 s42, s38, 16
	s_ashr_i32 s42, s42, 2
	s_add_i32 s42, s42, 1
	s_cmp_lt_i32 s38, 16
	s_cselect_b32 s42, 0, s42
	s_mul_i32 s42, s42, 0x1600
	s_lshl_b32 s39, s39, 7
	s_add_i32 s42, s42, s39
	s_lshl_b32 s42, s42, 2
	v_add_u32_e32 v26, s42, v3
	s_nop 0
	global_load_dword v16, v26, s[40:41]
.Lepi4_bw:
	s_waitcnt vmcnt(0)
	s_mul_i32 s37, s68, 0
	s_add_i32 s37, s37, s30
	s_cmp_lt_u32 s37, 0x2c0
	s_cbranch_scc0 .Lepi4_done
	ds_write_b32 v5, v10
	s_mul_i32 s37, s68, 1
	s_add_i32 s37, s37, s30
	s_cmp_lt_u32 s37, 0x2c0
	s_cbranch_scc0 .Lepi4_done
	ds_write_b32 v5, v11 offset:1024
	s_mul_i32 s37, s68, 2
	s_add_i32 s37, s37, s30
	s_cmp_lt_u32 s37, 0x2c0
	s_cbranch_scc0 .Lepi4_done
	ds_write_b32 v5, v12 offset:2048
	s_mul_i32 s37, s68, 3
	s_add_i32 s37, s37, s30
	s_cmp_lt_u32 s37, 0x2c0
	s_cbranch_scc0 .Lepi4_done
	ds_write_b32 v5, v13 offset:3072
	s_mul_i32 s37, s68, 4
	s_add_i32 s37, s37, s30
	s_cmp_lt_u32 s37, 0x2c0
	s_cbranch_scc0 .Lepi4_done
	ds_write_b32 v5, v14 offset:4096
	s_mul_i32 s37, s68, 5
	s_add_i32 s37, s37, s30
	s_cmp_lt_u32 s37, 0x2c0
	s_cbranch_scc0 .Lepi4_done
	ds_write_b32 v5, v15 offset:5120
	s_mul_i32 s37, s68, 6
	s_add_i32 s37, s37, s30
	s_cmp_lt_u32 s37, 0x2c0
	s_cbranch_scc0 .Lepi4_done
	ds_write_b32 v5, v16 offset:6144
.Lepi4_done:
	s_waitcnt vmcnt(0) lgkmcnt(0)
.LBB0_151:
	v_mov_b32_e32 v6, v228
	s_waitcnt lgkmcnt(0)
	s_barrier
	s_andn2_b64 vcc, exec, s[0:1]
	v_readfirstlane_b32 s52, v6
	s_cbranch_vccnz .LBB0_163
	v_lshlrev_b32_e32 v3, 4, v6
	v_add_u32_e32 v1, 0x2000, v3
	v_ashrrev_i32_e32 v0, 31, v1
	v_lshrrev_b32_e32 v0, 22, v0
	v_add_u32_e32 v0, v1, v0
	v_ashrrev_i32_e32 v0, 10, v0
	v_mul_i32_i24_e32 v2, 0x400, v0
	v_sub_u32_e32 v1, v1, v2
	v_lshrrev_b32_e32 v2, 4, v1
	v_bitop3_b32 v2, v2, v1, 32 bitop3:0x6c
	v_ashrrev_i32_e32 v1, 31, v2
	v_lshrrev_b32_e32 v1, 26, v1
	s_ashr_i32 s1, s52, 6
	v_readlane_b32 s28, v255, 36
	v_readlane_b32 s36, v254, 57
	v_add_u32_e32 v4, v2, v1
	v_lshlrev_b32_e32 v5, 3, v0
	s_ashr_i32 s2, s52, 8
	s_lshl_b32 s53, s1, 10
	s_mul_i32 s3, s28, 0xb00000
	v_readlane_b32 s42, v254, 63
	v_ashrrev_i32_e32 v1, 6, v4
	v_and_b32_e32 v5, -16, v5
	s_mul_hi_i32 s0, s28, 0xb00000
	v_readlane_b32 s43, v255, 0
	s_add_u32 s54, s42, s3
	v_add_u32_e32 v5, v1, v5
	s_addc_u32 s55, s43, s0
	v_and_b32_e32 v7, 3, v1
	s_mov_b32 s0, 0x1fffe0
	v_lshrrev_b32_e32 v8, 2, v5
	v_lshlrev_b32_e32 v9, 1, v5
	v_and_b32_e32 v4, 0xc0, v4
	v_and_or_b32 v7, v5, s0, v7
	v_and_b32_e32 v8, 4, v8
	v_and_b32_e32 v9, 24, v9
	v_sub_u32_e32 v2, v2, v4
	v_or3_b32 v7, v7, v8, v9
	v_lshlrev_b32_e32 v8, 5, v0
	v_ashrrev_i16_sdwa v2, v249, sext(v2) dst_sel:DWORD dst_unused:UNUSED_PAD src0_sel:DWORD src1_sel:BYTE_0
	v_and_b32_e32 v8, 32, v8
	v_bfe_i32 v2, v2, 0, 16
	v_add_lshl_u32 v4, v8, v2, 1
	v_lshl_add_u32 v144, v7, 11, v4
	v_lshl_add_u32 v146, v5, 11, v4
	v_bfe_i32 v4, v6, 27, 1
	v_lshrrev_b32_e32 v4, 22, v4
	v_add_u32_e32 v4, v3, v4
	v_and_b32_e32 v4, 0xfffffc00, v4
	v_sub_u32_e32 v3, v3, v4
	v_lshrrev_b32_e32 v4, 4, v3
	v_bitop3_b32 v5, v4, v3, 32 bitop3:0x6c
	v_ashrrev_i32_e32 v4, 31, v6
	v_lshrrev_b32_e32 v4, 26, v4
	v_ashrrev_i32_e32 v3, 31, v5
	v_add_u32_e32 v4, v6, v4
	v_lshrrev_b32_e32 v3, 26, v3
	v_ashrrev_i32_e32 v4, 6, v4
	v_add_u32_e32 v7, v5, v3
	v_lshlrev_b32_e32 v8, 3, v4
	v_ashrrev_i32_e32 v3, 6, v7
	v_and_b32_e32 v8, -16, v8
	v_add_u32_e32 v8, v3, v8
	v_and_b32_e32 v9, 3, v3
	v_and_or_b32 v9, v8, s0, v9
	s_lshr_b32 s0, s33, 29
	s_add_i32 s0, s30, s0
	s_ashr_i32 s3, s0, 3
	s_and_b32 s0, s0, -8
	s_sub_i32 s0, s30, s0
	s_cmp_lt_i32 s0, 0
	s_movk_i32 s28, 0x59
	s_cselect_b32 s28, s28, 0x58
	s_mul_i32 s0, s0, s28
	s_add_i32 s0, s0, s3
	s_mul_hi_i32 s3, s0, 0x2e8ba2e9
	s_lshr_b32 s28, s3, 31
	s_ashr_i32 s3, s3, 4
	s_add_i32 s3, s3, s28
	s_lshl_b32 s28, s3, 2
	s_mulk_i32 s3, 0x58
	s_sub_i32 s3, s0, s3
	s_bfe_i32 s0, s3, 0x80000
	v_readlane_b32 s29, v255, 37
	s_bfe_u32 s0, s0, 0x2000d
	s_add_i32 s29, s3, s0
	s_bfe_i32 s0, s29, 0x80000
	s_and_b32 s29, s29, 0xfc
	s_sub_i32 s3, s3, s29
	v_readlane_b32 s44, v255, 1
	s_sext_i32_i16 s0, s0
	s_sext_i32_i8 s3, s3
	v_readlane_b32 s37, v254, 58
	v_readlane_b32 s45, v255, 2
	v_lshrrev_b32_e32 v10, 2, v8
	v_lshlrev_b32_e32 v11, 1, v8
	v_and_b32_e32 v7, 0xc0, v7
	s_lshr_b32 s0, s0, 2
	s_add_i32 s44, s28, s3
	v_and_b32_e32 v10, 4, v10
	v_and_b32_e32 v11, 24, v11
	v_sub_u32_e32 v5, v5, v7
	s_ashr_i32 s45, s44, 31
	s_bfe_i64 s[36:37], s[0:1], 0x100000
	v_readlane_b32 s48, v255, 5
	v_or3_b32 v9, v9, v10, v11
	v_lshlrev_b32_e32 v10, 5, v4
	v_ashrrev_i16_sdwa v5, v249, sext(v5) dst_sel:DWORD dst_unused:UNUSED_PAD src0_sel:DWORD src1_sel:BYTE_0
	s_lshl_b64 s[28:29], s[44:45], 19
	s_lshl_b64 s[36:37], s[36:37], 19
	v_readlane_b32 s49, v255, 6
	v_and_b32_e32 v10, 32, v10
	v_bfe_i32 v5, v5, 0, 16
	s_add_u32 s48, s54, s36
	v_readlane_b32 s46, v255, 3
	v_add_lshl_u32 v7, v10, v5, 1
	s_addc_u32 s49, s55, s37
	s_add_i32 s45, s53, 0x10000
	s_add_i32 s56, s53, 0x12000
	v_readlane_b32 s47, v255, 4
	v_lshl_add_u32 v200, v9, 11, v7
	s_mov_b32 m0, s45
	s_add_u32 s46, s14, s28
	global_load_lds_dwordx4 v200, s[48:49]
	s_mov_b32 m0, s56
	s_addc_u32 s47, s15, s29
	s_add_i32 s57, s53, 0x2000
	v_lshl_add_u32 v148, v8, 11, v7
	global_load_lds_dwordx4 v144, s[48:49]
	s_mov_b32 m0, s53
	s_add_u32 s28, s48, 0x40000
	global_load_lds_dwordx4 v148, s[46:47]
	s_mov_b32 m0, s57
	s_addc_u32 s29, s49, 0
	s_add_i32 s58, s53, 0x14000
	global_load_lds_dwordx4 v146, s[46:47]
	s_mov_b32 m0, s58
	s_add_i32 s59, s53, 0x16000
	global_load_lds_dwordx4 v200, s[28:29]
	s_mov_b32 m0, s59
	v_mov_b32_e32 v245, 0x24000
	global_load_lds_dwordx4 v144, s[28:29]
	s_add_u32 s28, s46, 0x40000
	s_addc_u32 s29, s47, 0
	s_add_i32 s60, s53, 0x4000
	s_mov_b32 m0, s60
	s_add_i32 s61, s53, 0x6000
	global_load_lds_dwordx4 v148, s[28:29]
	s_mov_b32 m0, s61
	v_mov_b32_e32 v247, 1
	global_load_lds_dwordx4 v146, s[28:29]
	s_cmp_lg_u32 s2, 1
	v_readlane_b32 s38, v254, 59
	v_readlane_b32 s39, v254, 60
	v_readlane_b32 s40, v254, 61
	v_readlane_b32 s41, v254, 62
	v_readlane_b32 s50, v255, 7
	v_readlane_b32 s51, v255, 8
	s_cbranch_scc1 .LBB0_154
	s_barrier

.LBB0_677:
	s_and_b64 vcc, exec, s[66:67]
	s_cbranch_vccz .LBB0_767
	v_readlane_b32 s0, v255, 36
	v_readlane_b32 s1, v255, 37
	s_ashr_i32 s1, s0, 31
	s_ashr_i32 s33, s30, 31
	v_writelane_b32 v255, s0, 36
	s_cmpk_lt_i32 s30, 0x160
	s_waitcnt lgkmcnt(0)
	v_mov_b32_e32 v1, v228
	v_writelane_b32 v255, s1, 37
	s_cselect_b64 s[2:3], -1, 0
	s_cmpk_gt_i32 s30, 0x15f
	s_cbranch_scc1 .LBB0_714
	v_readfirstlane_b32 s36, v228
	s_nop 3
	s_cmp_lt_u32 s36, 0x100
	s_cbranch_scc0 .Lepi0_bias
	s_mov_b32 s28, s30
	s_mov_b32 s29, 0
	v_lshlrev_b32_e32 v0, 7, v228
	v_lshl_add_u32 v3, v228, 2, v246
.Lepi0_rb:
	s_add_i32 s36, s29, 0
	s_cmp_lt_u32 s36, 7
	s_cbranch_scc0 .Lepi0_rl0
	s_mul_i32 s37, s68, 0
	s_add_i32 s37, s37, s28
	s_cmp_lt_u32 s37, 0x160
	s_cbranch_scc0 .Lepi0_rl0
	s_and_b32 s38, s37, 7
	s_lshl_b32 s38, s38, 2
	s_bfe_u32 s39, s37, 0x20003
	s_add_u32 s38, s38, s39
	s_lshl_b32 s38, s38, 15
	v_add_u32_e32 v2, s38, v0
	s_nop 0
	global_load_dwordx4 v[8:11], v2, s[16:17]
	global_load_dwordx4 v[12:15], v2, s[16:17] offset:16
	global_load_dwordx4 v[16:19], v2, s[16:17] offset:32
	global_load_dwordx4 v[20:23], v2, s[16:17] offset:48
	global_load_dwordx4 v[24:27], v2, s[16:17] offset:64
	global_load_dwordx4 v[28:31], v2, s[16:17] offset:80
	global_load_dwordx4 v[32:35], v2, s[16:17] offset:96
	global_load_dwordx4 v[36:39], v2, s[16:17] offset:112
.Lepi0_rl0:
	s_add_i32 s36, s29, 1
	s_cmp_lt_u32 s36, 7
	s_cbranch_scc0 .Lepi0_rl1
	s_mul_i32 s37, s68, 1
	s_add_i32 s37, s37, s28
	s_cmp_lt_u32 s37, 0x160
	s_cbranch_scc0 .Lepi0_rl1
	s_and_b32 s38, s37, 7
	s_lshl_b32 s38, s38, 2
	s_bfe_u32 s39, s37, 0x20003
	s_add_u32 s38, s38, s39
	s_lshl_b32 s38, s38, 15
	v_add_u32_e32 v2, s38, v0
	s_nop 0
	global_load_dwordx4 v[40:43], v2, s[16:17]
	global_load_dwordx4 v[44:47], v2, s[16:17] offset:16
	global_load_dwordx4 v[48:51], v2, s[16:17] offset:32
	global_load_dwordx4 v[52:55], v2, s[16:17] offset:48
	global_load_dwordx4 v[56:59], v2, s[16:17] offset:64
	global_load_dwordx4 v[60:63], v2, s[16:17] offset:80
	global_load_dwordx4 v[64:67], v2, s[16:17] offset:96
	global_load_dwordx4 v[68:71], v2, s[16:17] offset:112
.Lepi0_rl1:
	s_add_i32 s36, s29, 2
	s_cmp_lt_u32 s36, 7
	s_cbranch_scc0 .Lepi0_rl2
	s_mul_i32 s37, s68, 2
	s_add_i32 s37, s37, s28
	s_cmp_lt_u32 s37, 0x160
	s_cbranch_scc0 .Lepi0_rl2
	s_and_b32 s38, s37, 7
	s_lshl_b32 s38, s38, 2
	s_bfe_u32 s39, s37, 0x20003
	s_add_u32 s38, s38, s39
	s_lshl_b32 s38, s38, 15
	v_add_u32_e32 v2, s38, v0
	s_nop 0
	global_load_dwordx4 v[72:75], v2, s[16:17]
	global_load_dwordx4 v[76:79], v2, s[16:17] offset:16
	global_load_dwordx4 v[80:83], v2, s[16:17] offset:32
	global_load_dwordx4 v[84:87], v2, s[16:17] offset:48
	global_load_dwordx4 v[88:91], v2, s[16:17] offset:64
	global_load_dwordx4 v[92:95], v2, s[16:17] offset:80
	global_load_dwordx4 v[96:99], v2, s[16:17] offset:96
	global_load_dwordx4 v[100:103], v2, s[16:17] offset:112
.Lepi0_rl2:
	s_waitcnt vmcnt(0)
	s_add_i32 s36, s29, 0
	s_cmp_lt_u32 s36, 7
	s_cbranch_scc0 .Lepi0_rs0
	s_mul_i32 s37, s68, 0
	s_add_i32 s37, s37, s28
	s_cmp_lt_u32 s37, 0x160
	s_cbranch_scc0 .Lepi0_rs0
	v_add_f32_e32 v8, v8, v24
	v_add_f32_e32 v9, v9, v25
	v_add_f32_e32 v10, v10, v26
	v_add_f32_e32 v11, v11, v27
	v_add_f32_e32 v12, v12, v28
	v_add_f32_e32 v13, v13, v29
	v_add_f32_e32 v14, v14, v30
	v_add_f32_e32 v15, v15, v31
	v_add_f32_e32 v16, v16, v32
	v_add_f32_e32 v17, v17, v33
	v_add_f32_e32 v18, v18, v34
	v_add_f32_e32 v19, v19, v35
	v_add_f32_e32 v20, v20, v36
	v_add_f32_e32 v21, v21, v37
	v_add_f32_e32 v22, v22, v38
	v_add_f32_e32 v23, v23, v39
	v_add_f32_e32 v8, v8, v16
	v_add_f32_e32 v9, v9, v17
	v_add_f32_e32 v10, v10, v18
	v_add_f32_e32 v11, v11, v19
	v_add_f32_e32 v12, v12, v20
	v_add_f32_e32 v13, v13, v21
	v_add_f32_e32 v14, v14, v22
	v_add_f32_e32 v15, v15, v23
	v_add_f32_e32 v8, v8, v12
	v_add_f32_e32 v9, v9, v13
	v_add_f32_e32 v10, v10, v14
	v_add_f32_e32 v11, v11, v15
	v_add_f32_e32 v8, v8, v10
	v_add_f32_e32 v9, v9, v11
	v_add_f32_e32 v8, v8, v9
	v_fmamk_f32 v1, v8, 0x3a800000, v250
	v_cmp_gt_f32_e32 vcc, s94, v1
	v_mul_f32_e32 v4, 0x4b800000, v1
	s_nop 1
	v_cndmask_b32_e32 v1, v1, v4, vcc
	v_rsq_f32_e32 v1, v1
	s_lshl_b32 s36, s36, 10
	v_add_u32_e32 v5, s36, v3
	v_mul_f32_e32 v4, 0x45800000, v1
	v_cndmask_b32_e32 v1, v1, v4, vcc
	ds_write_b32 v5, v1
.Lepi0_rs0:
	s_add_i32 s36, s29, 1
	s_cmp_lt_u32 s36, 7
	s_cbranch_scc0 .Lepi0_rs1
	s_mul_i32 s37, s68, 1
	s_add_i32 s37, s37, s28
	s_cmp_lt_u32 s37, 0x160
	s_cbranch_scc0 .Lepi0_rs1
	v_add_f32_e32 v40, v40, v56
	v_add_f32_e32 v41, v41, v57
	v_add_f32_e32 v42, v42, v58
	v_add_f32_e32 v43, v43, v59
	v_add_f32_e32 v44, v44, v60
	v_add_f32_e32 v45, v45, v61
	v_add_f32_e32 v46, v46, v62
	v_add_f32_e32 v47, v47, v63
	v_add_f32_e32 v48, v48, v64
	v_add_f32_e32 v49, v49, v65
	v_add_f32_e32 v50, v50, v66
	v_add_f32_e32 v51, v51, v67
	v_add_f32_e32 v52, v52, v68
	v_add_f32_e32 v53, v53, v69
	v_add_f32_e32 v54, v54, v70
	v_add_f32_e32 v55, v55, v71
	v_add_f32_e32 v40, v40, v48
	v_add_f32_e32 v41, v41, v49
	v_add_f32_e32 v42, v42, v50
	v_add_f32_e32 v43, v43, v51
	v_add_f32_e32 v44, v44, v52
	v_add_f32_e32 v45, v45, v53
	v_add_f32_e32 v46, v46, v54
	v_add_f32_e32 v47, v47, v55
	v_add_f32_e32 v40, v40, v44
	v_add_f32_e32 v41, v41, v45
	v_add_f32_e32 v42, v42, v46
	v_add_f32_e32 v43, v43, v47
	v_add_f32_e32 v40, v40, v42
	v_add_f32_e32 v41, v41, v43
	v_add_f32_e32 v40, v40, v41
	v_fmamk_f32 v1, v40, 0x3a800000, v250
	v_cmp_gt_f32_e32 vcc, s94, v1
	v_mul_f32_e32 v4, 0x4b800000, v1
	s_nop 1
	v_cndmask_b32_e32 v1, v1, v4, vcc
	v_rsq_f32_e32 v1, v1
	s_lshl_b32 s36, s36, 10
	v_add_u32_e32 v5, s36, v3
	v_mul_f32_e32 v4, 0x45800000, v1
	v_cndmask_b32_e32 v1, v1, v4, vcc
	ds_write_b32 v5, v1
.Lepi0_rs1:
	s_add_i32 s36, s29, 2
	s_cmp_lt_u32 s36, 7
	s_cbranch_scc0 .Lepi0_rs2
	s_mul_i32 s37, s68, 2
	s_add_i32 s37, s37, s28
	s_cmp_lt_u32 s37, 0x160
	s_cbranch_scc0 .Lepi0_rs2
	v_add_f32_e32 v72, v72, v88
	v_add_f32_e32 v73, v73, v89
	v_add_f32_e32 v74, v74, v90
	v_add_f32_e32 v75, v75, v91
	v_add_f32_e32 v76, v76, v92
	v_add_f32_e32 v77, v77, v93
	v_add_f32_e32 v78, v78, v94
	v_add_f32_e32 v79, v79, v95
	v_add_f32_e32 v80, v80, v96
	v_add_f32_e32 v81, v81, v97
	v_add_f32_e32 v82, v82, v98
	v_add_f32_e32 v83, v83, v99
	v_add_f32_e32 v84, v84, v100
	v_add_f32_e32 v85, v85, v101
	v_add_f32_e32 v86, v86, v102
	v_add_f32_e32 v87, v87, v103
	v_add_f32_e32 v72, v72, v80
	v_add_f32_e32 v73, v73, v81
	v_add_f32_e32 v74, v74, v82
	v_add_f32_e32 v75, v75, v83
	v_add_f32_e32 v76, v76, v84
	v_add_f32_e32 v77, v77, v85
	v_add_f32_e32 v78, v78, v86
	v_add_f32_e32 v79, v79, v87
	v_add_f32_e32 v72, v72, v76
	v_add_f32_e32 v73, v73, v77
	v_add_f32_e32 v74, v74, v78
	v_add_f32_e32 v75, v75, v79
	v_add_f32_e32 v72, v72, v74
	v_add_f32_e32 v73, v73, v75
	v_add_f32_e32 v72, v72, v73
	v_fmamk_f32 v1, v72, 0x3a800000, v250
	v_cmp_gt_f32_e32 vcc, s94, v1
	v_mul_f32_e32 v4, 0x4b800000, v1
	s_nop 1
	v_cndmask_b32_e32 v1, v1, v4, vcc
	v_rsq_f32_e32 v1, v1
	s_lshl_b32 s36, s36, 10
	v_add_u32_e32 v5, s36, v3
	v_mul_f32_e32 v4, 0x45800000, v1
	v_cndmask_b32_e32 v1, v1, v4, vcc
	ds_write_b32 v5, v1
.Lepi0_rs2:
	s_add_i32 s29, s29, 3
	s_mul_i32 s36, s68, 3
	s_add_i32 s28, s28, s36
	s_cmp_lt_u32 s29, 7
	s_cbranch_scc0 .Lepi0_done
	s_cmp_lt_u32 s28, 0x160
	s_cbranch_scc1 .Lepi0_rb
	s_branch .Lepi0_done
.Lepi0_bias:
	v_readlane_b32 s36, v255, 36
	s_nop 3
	s_mul_i32 s36, s36, 0xdc00
	s_add_u32 s40, s8, s36
	s_addc_u32 s41, s9, 0
	v_add_u32_e32 v2, 0xffffff00, v228
	v_lshlrev_b32_e32 v3, 2, v2
	v_lshl_add_u32 v5, v2, 2, v246
	v_add_u32_e32 v5, 0x1c00, v5
	s_mul_i32 s37, s68, 0
	s_add_i32 s37, s37, s30
	s_cmp_lt_u32 s37, 0x160
	s_cbranch_scc0 .Lepi0_bw
	s_and_b32 s38, s37, 7
	s_lshl_b32 s38, s38, 2
	s_bfe_u32 s39, s37, 0x20003
	s_add_u32 s38, s38, s39
	s_lshr_b32 s39, s37, 5
	s_sub_i32 s42, s38, 16
	s_ashr_i32 s42, s42, 2
	s_add_i32 s42, s42, 1
	s_cmp_lt_i32 s38, 16
	s_cselect_b32 s42, 0, s42
	s_mul_i32 s42, s42, 0xb00
	s_lshl_b32 s39, s39, 8
	s_add_i32 s42, s42, s39
	s_lshl_b32 s42, s42, 2
	v_add_u32_e32 v20, s42, v3
	s_nop 0
	global_load_dword v10, v20, s[40:41]
	s_mul_i32 s37, s68, 1
	s_add_i32 s37, s37, s30
	s_cmp_lt_u32 s37, 0x160
	s_cbranch_scc0 .Lepi0_bw
	s_and_b32 s38, s37, 7
	s_lshl_b32 s38, s38, 2
	s_bfe_u32 s39, s37, 0x20003
	s_add_u32 s38, s38, s39
	s_lshr_b32 s39, s37, 5
	s_sub_i32 s42, s38, 16
	s_ashr_i32 s42, s42, 2
	s_add_i32 s42, s42, 1
	s_cmp_lt_i32 s38, 16
	s_cselect_b32 s42, 0, s42
	s_mul_i32 s42, s42, 0xb00
	s_lshl_b32 s39, s39, 8
	s_add_i32 s42, s42, s39
	s_lshl_b32 s42, s42, 2
	v_add_u32_e32 v21, s42, v3
	s_nop 0
	global_load_dword v11, v21, s[40:41]
	s_mul_i32 s37, s68, 2
	s_add_i32 s37, s37, s30
	s_cmp_lt_u32 s37, 0x160
	s_cbranch_scc0 .Lepi0_bw
	s_and_b32 s38, s37, 7
	s_lshl_b32 s38, s38, 2
	s_bfe_u32 s39, s37, 0x20003
	s_add_u32 s38, s38, s39
	s_lshr_b32 s39, s37, 5
	s_sub_i32 s42, s38, 16
	s_ashr_i32 s42, s42, 2
	s_add_i32 s42, s42, 1
	s_cmp_lt_i32 s38, 16
	s_cselect_b32 s42, 0, s42
	s_mul_i32 s42, s42, 0xb00
	s_lshl_b32 s39, s39, 8
	s_add_i32 s42, s42, s39
	s_lshl_b32 s42, s42, 2
	v_add_u32_e32 v22, s42, v3
	s_nop 0
	global_load_dword v12, v22, s[40:41]
	s_mul_i32 s37, s68, 3
	s_add_i32 s37, s37, s30
	s_cmp_lt_u32 s37, 0x160
	s_cbranch_scc0 .Lepi0_bw
	s_and_b32 s38, s37, 7
	s_lshl_b32 s38, s38, 2
	s_bfe_u32 s39, s37, 0x20003
	s_add_u32 s38, s38, s39
	s_lshr_b32 s39, s37, 5
	s_sub_i32 s42, s38, 16
	s_ashr_i32 s42, s42, 2
	s_add_i32 s42, s42, 1
	s_cmp_lt_i32 s38, 16
	s_cselect_b32 s42, 0, s42
	s_mul_i32 s42, s42, 0xb00
	s_lshl_b32 s39, s39, 8
	s_add_i32 s42, s42, s39
	s_lshl_b32 s42, s42, 2
	v_add_u32_e32 v23, s42, v3
	s_nop 0
	global_load_dword v13, v23, s[40:41]
	s_mul_i32 s37, s68, 4
	s_add_i32 s37, s37, s30
	s_cmp_lt_u32 s37, 0x160
	s_cbranch_scc0 .Lepi0_bw
	s_and_b32 s38, s37, 7
	s_lshl_b32 s38, s38, 2
	s_bfe_u32 s39, s37, 0x20003
	s_add_u32 s38, s38, s39
	s_lshr_b32 s39, s37, 5
	s_sub_i32 s42, s38, 16
	s_ashr_i32 s42, s42, 2
	s_add_i32 s42, s42, 1
	s_cmp_lt_i32 s38, 16
	s_cselect_b32 s42, 0, s42
	s_mul_i32 s42, s42, 0xb00
	s_lshl_b32 s39, s39, 8
	s_add_i32 s42, s42, s39
	s_lshl_b32 s42, s42, 2
	v_add_u32_e32 v24, s42, v3
	s_nop 0
	global_load_dword v14, v24, s[40:41]
	s_mul_i32 s37, s68, 5
	s_add_i32 s37, s37, s30
	s_cmp_lt_u32 s37, 0x160
	s_cbranch_scc0 .Lepi0_bw
	s_and_b32 s38, s37, 7
	s_lshl_b32 s38, s38, 2
	s_bfe_u32 s39, s37, 0x20003
	s_add_u32 s38, s38, s39
	s_lshr_b32 s39, s37, 5
	s_sub_i32 s42, s38, 16
	s_ashr_i32 s42, s42, 2
	s_add_i32 s42, s42, 1
	s_cmp_lt_i32 s38, 16
	s_cselect_b32 s42, 0, s42
	s_mul_i32 s42, s42, 0xb00
	s_lshl_b32 s39, s39, 8
	s_add_i32 s42, s42, s39
	s_lshl_b32 s42, s42, 2
	v_add_u32_e32 v25, s42, v3
	s_nop 0
	global_load_dword v15, v25, s[40:41]
	s_mul_i32 s37, s68, 6
	s_add_i32 s37, s37, s30
	s_cmp_lt_u32 s37, 0x160
	s_cbranch_scc0 .Lepi0_bw
	s_and_b32 s38, s37, 7
	s_lshl_b32 s38, s38, 2
	s_bfe_u32 s39, s37, 0x20003
	s_add_u32 s38, s38, s39
	s_lshr_b32 s39, s37, 5
	s_sub_i32 s42, s38, 16
	s_ashr_i32 s42, s42, 2
	s_add_i32 s42, s42, 1
	s_cmp_lt_i32 s38, 16
	s_cselect_b32 s42, 0, s42
	s_mul_i32 s42, s42, 0xb00
	s_lshl_b32 s39, s39, 8
	s_add_i32 s42, s42, s39
	s_lshl_b32 s42, s42, 2
	v_add_u32_e32 v26, s42, v3
	s_nop 0
	global_load_dword v16, v26, s[40:41]
.Lepi0_bw:
	s_waitcnt vmcnt(0)
	s_mul_i32 s37, s68, 0
	s_add_i32 s37, s37, s30
	s_cmp_lt_u32 s37, 0x160
	s_cbranch_scc0 .Lepi0_done
	ds_write_b32 v5, v10
	s_mul_i32 s37, s68, 1
	s_add_i32 s37, s37, s30
	s_cmp_lt_u32 s37, 0x160
	s_cbranch_scc0 .Lepi0_done
	ds_write_b32 v5, v11 offset:1024
	s_mul_i32 s37, s68, 2
	s_add_i32 s37, s37, s30
	s_cmp_lt_u32 s37, 0x160
	s_cbranch_scc0 .Lepi0_done
	ds_write_b32 v5, v12 offset:2048
	s_mul_i32 s37, s68, 3
	s_add_i32 s37, s37, s30
	s_cmp_lt_u32 s37, 0x160
	s_cbranch_scc0 .Lepi0_done
	ds_write_b32 v5, v13 offset:3072
	s_mul_i32 s37, s68, 4
	s_add_i32 s37, s37, s30
	s_cmp_lt_u32 s37, 0x160
	s_cbranch_scc0 .Lepi0_done
	ds_write_b32 v5, v14 offset:4096
	s_mul_i32 s37, s68, 5
	s_add_i32 s37, s37, s30
	s_cmp_lt_u32 s37, 0x160
	s_cbranch_scc0 .Lepi0_done
	ds_write_b32 v5, v15 offset:5120
	s_mul_i32 s37, s68, 6
	s_add_i32 s37, s37, s30
	s_cmp_lt_u32 s37, 0x160
	s_cbranch_scc0 .Lepi0_done
	ds_write_b32 v5, v16 offset:6144
.Lepi0_done:
	s_waitcnt vmcnt(0) lgkmcnt(0)
.LBB0_714:
	v_readlane_b32 s0, v255, 36
	v_readlane_b32 s36, v254, 57
	s_mul_i32 s76, s0, 0x580000
	v_readlane_b32 s38, v254, 59
	v_readlane_b32 s1, v255, 37
	s_mul_hi_i32 s75, s0, 0x580000
	v_readlane_b32 s39, v254, 60
	s_add_u32 s0, s38, s76
	v_mov_b32_e32 v6, v228
	s_addc_u32 s1, s39, s75
	s_waitcnt vmcnt(0) lgkmcnt(0)
	s_barrier
	s_andn2_b64 vcc, exec, s[2:3]
	v_readfirstlane_b32 s52, v6
	v_readlane_b32 s37, v254, 58
	v_readlane_b32 s40, v254, 61
	v_readlane_b32 s41, v254, 62
	v_readlane_b32 s42, v254, 63
	v_readlane_b32 s43, v255, 0
	v_readlane_b32 s44, v255, 1
	v_readlane_b32 s45, v255, 2
	v_readlane_b32 s46, v255, 3
	v_readlane_b32 s47, v255, 4
	v_readlane_b32 s48, v255, 5
	v_readlane_b32 s49, v255, 6
	v_readlane_b32 s50, v255, 7
	v_readlane_b32 s51, v255, 8
	s_cbranch_vccnz .LBB0_726
	v_lshlrev_b32_e32 v3, 4, v6
	v_add_u32_e32 v1, 0x2000, v3
	v_ashrrev_i32_e32 v0, 31, v1
	v_lshrrev_b32_e32 v0, 22, v0
	v_add_u32_e32 v0, v1, v0
	v_ashrrev_i32_e32 v0, 10, v0
	v_mul_i32_i24_e32 v2, 0x400, v0
	v_sub_u32_e32 v1, v1, v2
	v_lshrrev_b32_e32 v2, 4, v1
	v_bitop3_b32 v2, v2, v1, 32 bitop3:0x6c
	v_ashrrev_i32_e32 v1, 31, v2
	v_lshrrev_b32_e32 v1, 26, v1
	v_add_u32_e32 v4, v2, v1
	v_lshlrev_b32_e32 v5, 3, v0
	v_ashrrev_i32_e32 v1, 6, v4
	v_and_b32_e32 v5, -16, v5
	v_add_u32_e32 v5, v1, v5
	v_and_b32_e32 v7, 3, v1
	s_mov_b32 s2, 0x1fffe0
	v_lshrrev_b32_e32 v8, 2, v5
	v_lshlrev_b32_e32 v9, 1, v5
	v_and_b32_e32 v4, 0xc0, v4
	v_and_or_b32 v7, v5, s2, v7
	v_and_b32_e32 v8, 4, v8
	v_and_b32_e32 v9, 24, v9
	v_sub_u32_e32 v2, v2, v4
	v_or3_b32 v7, v7, v8, v9
	v_lshlrev_b32_e32 v8, 5, v0
	v_ashrrev_i16_sdwa v2, v249, sext(v2) dst_sel:DWORD dst_unused:UNUSED_PAD src0_sel:DWORD src1_sel:BYTE_0
	v_and_b32_e32 v8, 32, v8
	v_bfe_i32 v2, v2, 0, 16
	v_add_lshl_u32 v4, v8, v2, 1
	v_lshl_add_u32 v144, v7, 11, v4
	v_lshl_add_u32 v146, v5, 11, v4
	v_bfe_i32 v4, v6, 27, 1
	v_lshrrev_b32_e32 v4, 22, v4
	v_add_u32_e32 v4, v3, v4
	v_and_b32_e32 v4, 0xfffffc00, v4
	v_sub_u32_e32 v3, v3, v4
	v_lshrrev_b32_e32 v4, 4, v3
	v_bitop3_b32 v5, v4, v3, 32 bitop3:0x6c
	v_ashrrev_i32_e32 v4, 31, v6
	v_lshrrev_b32_e32 v4, 26, v4
	v_ashrrev_i32_e32 v3, 31, v5
	v_add_u32_e32 v4, v6, v4
	v_lshrrev_b32_e32 v3, 26, v3
	v_ashrrev_i32_e32 v4, 6, v4
	v_add_u32_e32 v7, v5, v3
	v_lshlrev_b32_e32 v8, 3, v4
	v_ashrrev_i32_e32 v3, 6, v7
	v_and_b32_e32 v8, -16, v8
	v_add_u32_e32 v8, v3, v8
	v_and_b32_e32 v9, 3, v3
	v_and_or_b32 v9, v8, s2, v9
	s_lshr_b32 s2, s33, 29
	s_add_i32 s2, s30, s2
	s_ashr_i32 s3, s52, 6
	s_ashr_i32 s28, s2, 3
	s_and_b32 s2, s2, -8
	s_ashr_i32 s29, s52, 8
	s_lshl_b32 s53, s3, 10
	s_sub_i32 s2, s30, s2
	s_cmp_lt_i32 s2, 0
	s_cselect_b32 s36, 45, 44
	s_mul_i32 s2, s2, s36
	s_add_i32 s2, s2, s28
	s_mul_hi_i32 s28, s2, 0x2e8ba2e9
	s_lshr_b32 s36, s28, 31
	s_ashr_i32 s28, s28, 3
	s_add_i32 s28, s28, s36
	s_lshl_b32 s36, s28, 2
	s_mul_i32 s28, s28, 44
	s_sub_i32 s28, s2, s28
	s_bfe_i32 s2, s28, 0x80000
	s_bfe_u32 s2, s2, 0x2000d
	s_add_i32 s37, s28, s2
	s_bfe_i32 s2, s37, 0x80000
	s_and_b32 s37, s37, 0xfc
	s_sub_i32 s28, s28, s37
	s_sext_i32_i16 s2, s2
	s_sext_i32_i8 s28, s28
	v_lshrrev_b32_e32 v10, 2, v8
	v_lshlrev_b32_e32 v11, 1, v8
	v_and_b32_e32 v7, 0xc0, v7
	s_lshr_b32 s2, s2, 2
	s_add_i32 s40, s36, s28
	v_and_b32_e32 v10, 4, v10
	v_and_b32_e32 v11, 24, v11
	v_sub_u32_e32 v5, v5, v7
	s_ashr_i32 s41, s40, 31
	s_bfe_i64 s[38:39], s[2:3], 0x100000
	v_or3_b32 v9, v9, v10, v11
	v_lshlrev_b32_e32 v10, 5, v4
	v_ashrrev_i16_sdwa v5, v249, sext(v5) dst_sel:DWORD dst_unused:UNUSED_PAD src0_sel:DWORD src1_sel:BYTE_0
	s_lshl_b64 s[36:37], s[40:41], 19
	s_lshl_b64 s[38:39], s[38:39], 19
	v_and_b32_e32 v10, 32, v10
	v_bfe_i32 v5, v5, 0, 16
	s_add_u32 s48, s0, s38
	v_add_lshl_u32 v7, v10, v5, 1
	s_addc_u32 s49, s1, s39
	s_add_i32 s41, s53, 0x10000
	s_add_i32 s56, s53, 0x12000
	v_lshl_add_u32 v200, v9, 11, v7
	s_mov_b32 m0, s41
	s_add_u32 s46, s14, s36
	global_load_lds_dwordx4 v200, s[48:49]
	s_mov_b32 m0, s56
	s_addc_u32 s47, s15, s37
	s_add_i32 s57, s53, 0x2000
	v_lshl_add_u32 v148, v8, 11, v7
	global_load_lds_dwordx4 v144, s[48:49]
	s_mov_b32 m0, s53
	s_add_u32 s36, s48, 0x40000
	global_load_lds_dwordx4 v148, s[46:47]
	s_mov_b32 m0, s57
	s_addc_u32 s37, s49, 0
	s_add_i32 s58, s53, 0x14000
	global_load_lds_dwordx4 v146, s[46:47]
	s_mov_b32 m0, s58
	s_add_i32 s59, s53, 0x16000
	global_load_lds_dwordx4 v200, s[36:37]
	s_mov_b32 m0, s59
	s_nop 0
	global_load_lds_dwordx4 v144, s[36:37]
	s_add_u32 s36, s46, 0x40000
	s_addc_u32 s37, s47, 0
	s_add_i32 s60, s53, 0x4000
	s_mov_b32 m0, s60
	s_add_i32 s61, s53, 0x6000
	global_load_lds_dwordx4 v148, s[36:37]
	s_mov_b32 m0, s61
	s_cmp_lg_u32 s29, 1
	global_load_lds_dwordx4 v146, s[36:37]
	s_cbranch_scc1 .LBB0_717
	s_barrier
